# norm loops (phases 5,8,17,20): all 8 row loads issued up front with counted vmcnt waits instead of a wait after every 1-2 loads
# speedup vs baseline: 1.0055x; 1.0055x over previous
.LBB0_18:
	global_load_dwordx4 v[38:41], v[66:67], off
	global_load_dwordx4 v[34:37], v[66:67], off offset:1024
	global_load_dwordx4 v[46:49], v[66:67], off offset:2048
	global_load_dwordx4 v[50:53], v[66:67], off offset:3072
	v_add_co_u32_e32 v68, vcc, s33, v66
	v_add_u32_e32 v0, 0x800, v0
	s_nop 0
	v_addc_co_u32_e32 v69, vcc, 0, v67, vcc
	global_load_dwordx4 v[42:45], v[68:69], off
	global_load_dwordx4 v[58:61], v[68:69], off offset:1024
	global_load_dwordx4 v[54:57], v[68:69], off offset:2048
	global_load_dwordx4 v[62:65], v[68:69], off offset:3072
	s_waitcnt vmcnt(7)
	v_mul_f32_e32 v70, v38, v38
	v_mul_f32_e32 v71, v40, v40
	v_fmac_f32_e32 v70, v39, v39
	v_fmac_f32_e32 v71, v41, v41
	v_add_f32_e32 v70, v70, v71
	s_waitcnt vmcnt(6)
	v_mul_f32_e32 v71, v34, v34
	v_mul_f32_e32 v72, v36, v36
	v_fmac_f32_e32 v71, v35, v35
	v_fmac_f32_e32 v72, v37, v37
	v_add_f32_e32 v71, v71, v72
	v_add_f32_e32 v70, v70, v71
	s_waitcnt vmcnt(5)
	v_mul_f32_e32 v71, v46, v46
	v_mul_f32_e32 v72, v48, v48
	v_fmac_f32_e32 v71, v47, v47
	v_fmac_f32_e32 v72, v49, v49
	v_add_f32_e32 v71, v71, v72
	v_add_f32_e32 v70, v70, v71
	s_waitcnt vmcnt(4)
	v_mul_f32_e32 v71, v50, v50
	v_mul_f32_e32 v72, v52, v52
	v_fmac_f32_e32 v71, v51, v51
	v_fmac_f32_e32 v72, v53, v53
	v_add_f32_e32 v71, v71, v72
	v_add_f32_e32 v70, v70, v71
	s_waitcnt vmcnt(3)
	v_mul_f32_e32 v71, v42, v42
	v_mul_f32_e32 v72, v44, v44
	v_fmac_f32_e32 v71, v43, v43
	v_fmac_f32_e32 v72, v45, v45
	v_add_f32_e32 v71, v71, v72
	v_add_f32_e32 v70, v70, v71
	s_waitcnt vmcnt(2)
	v_mul_f32_e32 v71, v58, v58
	v_mul_f32_e32 v72, v60, v60
	v_fmac_f32_e32 v71, v59, v59
	v_fmac_f32_e32 v72, v61, v61
	v_add_f32_e32 v71, v71, v72
	v_add_f32_e32 v70, v70, v71
	s_waitcnt vmcnt(1)
	v_mul_f32_e32 v71, v54, v54
	v_mul_f32_e32 v72, v56, v56
	v_fmac_f32_e32 v71, v55, v55
	v_fmac_f32_e32 v72, v57, v57
	v_add_f32_e32 v71, v71, v72
	v_add_f32_e32 v70, v70, v71
	s_waitcnt vmcnt(0)
	v_mul_f32_e32 v71, v62, v62
	v_mul_f32_e32 v72, v64, v64
	v_fmac_f32_e32 v71, v63, v63
	v_fmac_f32_e32 v72, v65, v65
	v_add_f32_e32 v71, v71, v72
	v_add_f32_e32 v70, v70, v71
	s_nop 1
	v_add_f32_dpp v70, v70, v70 quad_perm:[1,0,3,2] row_mask:0xf bank_mask:0xf bound_ctrl:1
	s_nop 1
	v_add_f32_dpp v70, v70, v70 quad_perm:[2,3,0,1] row_mask:0xf bank_mask:0xf bound_ctrl:1
	s_nop 1
	v_add_f32_dpp v70, v70, v70 row_half_mirror row_mask:0xf bank_mask:0xf bound_ctrl:1
	s_nop 1
	v_add_f32_dpp v70, v70, v70 row_mirror row_mask:0xf bank_mask:0xf bound_ctrl:1
	s_nop 0
	v_readlane_b32 s10, v70, 16
	v_readlane_b32 s11, v70, 48
	v_readlane_b32 s8, v70, 0
	v_readlane_b32 s9, v70, 32
	v_mov_b32_e32 v70, s10
	v_mov_b32_e32 v71, s11
	v_pk_add_f32 v[70:71], s[8:9], v[70:71]
	s_nop 0
	v_add_f32_e32 v70, v70, v71
	v_fmamk_f32 v70, v70, 0x3a000000, v236
	v_cmp_gt_f32_e32 vcc, s13, v70
	v_mul_f32_e32 v71, 0x4b800000, v70
	s_nop 0
	v_cndmask_b32_e32 v70, v70, v71, vcc
	v_rsq_f32_e32 v70, v70
	s_nop 0
	v_mul_f32_e32 v71, 0x45800000, v70
	v_cndmask_b32_e32 v70, v70, v71, vcc
	v_pk_mul_f32 v[34:35], v[34:35], v[70:71] op_sel_hi:[1,0]
	v_pk_mul_f32 v[36:37], v[36:37], v[70:71] op_sel_hi:[1,0]
	v_pk_mul_f32 v[34:35], v[6:7], v[34:35]
	v_pk_mul_f32 v[36:37], v[8:9], v[36:37]
	global_store_dwordx4 v[66:67], v[34:37], off offset:1024
	v_pk_mul_f32 v[38:39], v[38:39], v[70:71] op_sel_hi:[1,0]
	v_pk_mul_f32 v[40:41], v[40:41], v[70:71] op_sel_hi:[1,0]
	v_pk_mul_f32 v[34:35], v[46:47], v[70:71] op_sel_hi:[1,0]
	v_pk_mul_f32 v[36:37], v[48:49], v[70:71] op_sel_hi:[1,0]
	v_pk_mul_f32 v[34:35], v[10:11], v[34:35]
	v_pk_mul_f32 v[36:37], v[12:13], v[36:37]
	global_store_dwordx4 v[66:67], v[34:37], off offset:2048
	v_pk_mul_f32 v[40:41], v[4:5], v[40:41]
	v_pk_mul_f32 v[38:39], v[2:3], v[38:39]
	v_pk_mul_f32 v[34:35], v[50:51], v[70:71] op_sel_hi:[1,0]
	v_pk_mul_f32 v[36:37], v[52:53], v[70:71] op_sel_hi:[1,0]
	v_pk_mul_f32 v[34:35], v[14:15], v[34:35]
	v_pk_mul_f32 v[36:37], v[16:17], v[36:37]
	global_store_dwordx4 v[66:67], v[34:37], off offset:3072
	v_cmp_lt_i32_e32 vcc, s89, v0
	global_store_dwordx4 v[66:67], v[38:41], off
	v_pk_mul_f32 v[34:35], v[42:43], v[70:71] op_sel_hi:[1,0]
	v_pk_mul_f32 v[36:37], v[44:45], v[70:71] op_sel_hi:[1,0]
	v_pk_mul_f32 v[34:35], v[18:19], v[34:35]
	v_pk_mul_f32 v[36:37], v[20:21], v[36:37]
	global_store_dwordx4 v[68:69], v[34:37], off
	v_lshl_add_u64 v[66:67], v[66:67], 0, s[40:41]
	s_or_b64 s[6:7], vcc, s[6:7]
	v_pk_mul_f32 v[34:35], v[58:59], v[70:71] op_sel_hi:[1,0]
	v_pk_mul_f32 v[36:37], v[60:61], v[70:71] op_sel_hi:[1,0]
	v_pk_mul_f32 v[34:35], v[22:23], v[34:35]
	v_pk_mul_f32 v[36:37], v[24:25], v[36:37]
	global_store_dwordx4 v[68:69], v[34:37], off offset:1024
	s_nop 1
	v_pk_mul_f32 v[34:35], v[54:55], v[70:71] op_sel_hi:[1,0]
	v_pk_mul_f32 v[36:37], v[56:57], v[70:71] op_sel_hi:[1,0]
	v_pk_mul_f32 v[34:35], v[26:27], v[34:35]
	v_pk_mul_f32 v[36:37], v[28:29], v[36:37]
	global_store_dwordx4 v[68:69], v[34:37], off offset:2048
	s_nop 1
	v_pk_mul_f32 v[34:35], v[62:63], v[70:71] op_sel_hi:[1,0]
	v_pk_mul_f32 v[36:37], v[64:65], v[70:71] op_sel_hi:[1,0]
	v_pk_mul_f32 v[34:35], v[30:31], v[34:35]
	v_pk_mul_f32 v[36:37], v[32:33], v[36:37]
	global_store_dwordx4 v[68:69], v[34:37], off offset:3072
	s_andn2_b64 exec, exec, s[6:7]
	s_cbranch_execnz .LBB0_18

.LBB0_62:
	v_add_u32_e32 v58, 0x800, v58
	global_load_dwordx4 v[38:41], v[54:55], off offset:-4096
	global_load_dwordx4 v[34:37], v[54:55], off offset:-3072
	global_load_dwordx4 v[42:45], v[54:55], off offset:-2048
	global_load_dwordx4 v[46:49], v[54:55], off offset:-1024
	global_load_dwordx4 v[60:63], v[54:55], off
	global_load_dwordx4 v[64:67], v[54:55], off offset:1024
	global_load_dwordx4 v[68:71], v[54:55], off offset:2048
	global_load_dwordx4 v[72:75], v[54:55], off offset:3072
	s_nop 0
	v_lshl_add_u64 v[54:55], v[54:55], 0, s[44:45]
	s_waitcnt vmcnt(7)
	v_mul_f32_e32 v51, v38, v38
	v_mul_f32_e32 v81, v40, v40
	v_fmac_f32_e32 v51, v39, v39
	v_fmac_f32_e32 v81, v41, v41
	v_add_f32_e32 v51, v51, v81
	s_waitcnt vmcnt(6)
	v_mul_f32_e32 v82, v34, v34
	v_mul_f32_e32 v81, v36, v36
	v_fmac_f32_e32 v82, v35, v35
	v_fmac_f32_e32 v81, v37, v37
	v_add_f32_e32 v82, v82, v81
	v_add_f32_e32 v51, v51, v82
	s_waitcnt vmcnt(5)
	v_mul_f32_e32 v82, v42, v42
	v_mul_f32_e32 v81, v44, v44
	v_fmac_f32_e32 v82, v43, v43
	v_fmac_f32_e32 v81, v45, v45
	v_add_f32_e32 v82, v82, v81
	v_add_f32_e32 v51, v51, v82
	s_waitcnt vmcnt(4)
	v_mul_f32_e32 v82, v46, v46
	v_mul_f32_e32 v81, v48, v48
	v_fmac_f32_e32 v82, v47, v47
	v_fmac_f32_e32 v81, v49, v49
	v_add_f32_e32 v82, v82, v81
	v_add_f32_e32 v51, v51, v82
	s_waitcnt vmcnt(3)
	v_mul_f32_e32 v82, v60, v60
	v_mul_f32_e32 v81, v62, v62
	v_fmac_f32_e32 v82, v61, v61
	v_fmac_f32_e32 v81, v63, v63
	v_add_f32_e32 v82, v82, v81
	v_add_f32_e32 v51, v51, v82
	s_waitcnt vmcnt(2)
	v_mul_f32_e32 v82, v64, v64
	v_mul_f32_e32 v81, v66, v66
	v_fmac_f32_e32 v82, v65, v65
	v_fmac_f32_e32 v81, v67, v67
	v_add_f32_e32 v82, v82, v81
	v_add_f32_e32 v51, v51, v82
	s_waitcnt vmcnt(1)
	v_mul_f32_e32 v82, v68, v68
	v_mul_f32_e32 v81, v70, v70
	v_fmac_f32_e32 v82, v69, v69
	v_fmac_f32_e32 v81, v71, v71
	v_add_f32_e32 v82, v82, v81
	v_add_f32_e32 v51, v51, v82
	s_waitcnt vmcnt(0)
	v_mul_f32_e32 v82, v72, v72
	v_mul_f32_e32 v81, v74, v74
	v_fmac_f32_e32 v82, v73, v73
	v_fmac_f32_e32 v81, v75, v75
	v_add_f32_e32 v82, v82, v81
	v_add_f32_e32 v51, v51, v82
	s_nop 1
	v_add_f32_dpp v51, v51, v51 quad_perm:[1,0,3,2] row_mask:0xf bank_mask:0xf bound_ctrl:1
	s_nop 1
	v_add_f32_dpp v51, v51, v51 quad_perm:[2,3,0,1] row_mask:0xf bank_mask:0xf bound_ctrl:1
	s_nop 1
	v_add_f32_dpp v51, v51, v51 row_half_mirror row_mask:0xf bank_mask:0xf bound_ctrl:1
	s_nop 1
	v_add_f32_dpp v51, v51, v51 row_mirror row_mask:0xf bank_mask:0xf bound_ctrl:1
	s_nop 0
	v_readlane_b32 s8, v51, 16
	v_readlane_b32 s9, v51, 48
	v_readlane_b32 s6, v51, 0
	v_readlane_b32 s7, v51, 32
	v_mov_b32_e32 v76, s8
	v_mov_b32_e32 v77, s9
	v_pk_add_f32 v[76:77], s[6:7], v[76:77]
	s_nop 0
	v_add_f32_e32 v51, v76, v77
	v_fmamk_f32 v51, v51, 0x3a000000, v236
	v_cmp_gt_f32_e32 vcc, s13, v51
	v_mul_f32_e32 v59, 0x4b800000, v51
	s_nop 0
	v_cndmask_b32_e32 v51, v51, v59, vcc
	v_rsq_f32_e32 v51, v51
	s_nop 0
	v_mul_f32_e32 v59, 0x45800000, v51
	v_cndmask_b32_e32 v76, v51, v59, vcc
	v_pk_mul_f32 v[38:39], v[38:39], v[76:77] op_sel_hi:[1,0]
	v_pk_mul_f32 v[34:35], v[34:35], v[76:77] op_sel_hi:[1,0]
	v_pk_mul_f32 v[40:41], v[40:41], v[76:77] op_sel_hi:[1,0]
	v_pk_mul_f32 v[38:39], v[10:11], v[38:39]
	v_pk_mul_f32 v[36:37], v[36:37], v[76:77] op_sel_hi:[1,0]
	v_pk_mul_f32 v[34:35], v[2:3], v[34:35]
	v_pk_mul_f32 v[40:41], v[12:13], v[40:41]
	v_cvt_pk_bf16_f32 v38, v38, v39
	v_pk_mul_f32 v[36:37], v[4:5], v[36:37]
	v_cvt_pk_bf16_f32 v39, v40, v41
	global_store_dwordx2 v[52:53], v[38:39], off
	v_cvt_pk_bf16_f32 v34, v34, v35
	v_cvt_pk_bf16_f32 v35, v36, v37
	global_store_dwordx2 v[52:53], v[34:35], off offset:512
	v_pk_mul_f32 v[34:35], v[42:43], v[76:77] op_sel_hi:[1,0]
	v_pk_mul_f32 v[36:37], v[44:45], v[76:77] op_sel_hi:[1,0]
	v_pk_mul_f32 v[34:35], v[6:7], v[34:35]
	v_pk_mul_f32 v[36:37], v[8:9], v[36:37]
	v_cvt_pk_bf16_f32 v34, v34, v35
	v_cmp_lt_i32_e32 vcc, s89, v58
	v_cvt_pk_bf16_f32 v35, v36, v37
	global_store_dwordx2 v[52:53], v[34:35], off offset:1024
	v_pk_mul_f32 v[34:35], v[46:47], v[76:77] op_sel_hi:[1,0]
	v_pk_mul_f32 v[36:37], v[48:49], v[76:77] op_sel_hi:[1,0]
	v_pk_mul_f32 v[34:35], v[14:15], v[34:35]
	v_pk_mul_f32 v[36:37], v[16:17], v[36:37]
	v_cvt_pk_bf16_f32 v34, v34, v35
	s_or_b64 s[40:41], vcc, s[40:41]
	v_cvt_pk_bf16_f32 v35, v36, v37
	global_store_dwordx2 v[52:53], v[34:35], off offset:1536
	v_pk_mul_f32 v[34:35], v[60:61], v[76:77] op_sel_hi:[1,0]
	v_pk_mul_f32 v[36:37], v[62:63], v[76:77] op_sel_hi:[1,0]
	v_pk_mul_f32 v[34:35], v[18:19], v[34:35]
	v_pk_mul_f32 v[36:37], v[20:21], v[36:37]
	v_cvt_pk_bf16_f32 v34, v34, v35
	s_nop 0
	v_cvt_pk_bf16_f32 v35, v36, v37
	global_store_dwordx2 v[52:53], v[34:35], off offset:2048
	v_pk_mul_f32 v[34:35], v[64:65], v[76:77] op_sel_hi:[1,0]
	v_pk_mul_f32 v[36:37], v[66:67], v[76:77] op_sel_hi:[1,0]
	v_pk_mul_f32 v[34:35], v[22:23], v[34:35]
	v_pk_mul_f32 v[36:37], v[24:25], v[36:37]
	v_cvt_pk_bf16_f32 v34, v34, v35
	s_nop 0
	v_cvt_pk_bf16_f32 v35, v36, v37
	global_store_dwordx2 v[52:53], v[34:35], off offset:2560
	v_pk_mul_f32 v[34:35], v[68:69], v[76:77] op_sel_hi:[1,0]
	v_pk_mul_f32 v[36:37], v[70:71], v[76:77] op_sel_hi:[1,0]
	v_pk_mul_f32 v[34:35], v[26:27], v[34:35]
	v_pk_mul_f32 v[36:37], v[28:29], v[36:37]
	v_cvt_pk_bf16_f32 v34, v34, v35
	s_nop 0
	v_cvt_pk_bf16_f32 v35, v36, v37
	global_store_dwordx2 v[52:53], v[34:35], off offset:3072
	v_pk_mul_f32 v[34:35], v[72:73], v[76:77] op_sel_hi:[1,0]
	v_pk_mul_f32 v[36:37], v[74:75], v[76:77] op_sel_hi:[1,0]
	v_pk_mul_f32 v[34:35], v[30:31], v[34:35]
	v_pk_mul_f32 v[36:37], v[32:33], v[36:37]
	v_cvt_pk_bf16_f32 v34, v34, v35
	s_nop 0
	v_cvt_pk_bf16_f32 v35, v36, v37
	global_store_dwordx2 v[52:53], v[34:35], off offset:3584
	v_lshl_add_u64 v[52:53], v[52:53], 0, s[46:47]
	s_andn2_b64 exec, exec, s[40:41]
	s_cbranch_execnz .LBB0_62

.LBB0_512:
	v_add_u32_e32 v0, 0x800, v0
	global_load_dwordx4 v[38:41], v[52:53], off offset:-4096
	global_load_dwordx4 v[34:37], v[52:53], off offset:-3072
	global_load_dwordx4 v[42:45], v[52:53], off offset:-2048
	global_load_dwordx4 v[46:49], v[52:53], off offset:-1024
	global_load_dwordx4 v[54:57], v[52:53], off
	global_load_dwordx4 v[58:61], v[52:53], off offset:1024
	global_load_dwordx4 v[62:65], v[52:53], off offset:2048
	global_load_dwordx4 v[66:69], v[52:53], off offset:3072
	s_nop 0
	v_lshl_add_u64 v[52:53], v[52:53], 0, s[42:43]
	s_waitcnt vmcnt(7)
	v_mul_f32_e32 v70, v38, v38
	v_mul_f32_e32 v76, v40, v40
	v_fmac_f32_e32 v70, v39, v39
	v_fmac_f32_e32 v76, v41, v41
	v_add_f32_e32 v70, v70, v76
	s_waitcnt vmcnt(6)
	v_mul_f32_e32 v77, v34, v34
	v_mul_f32_e32 v76, v36, v36
	v_fmac_f32_e32 v77, v35, v35
	v_fmac_f32_e32 v76, v37, v37
	v_add_f32_e32 v77, v77, v76
	v_add_f32_e32 v70, v70, v77
	s_waitcnt vmcnt(5)
	v_mul_f32_e32 v77, v42, v42
	v_mul_f32_e32 v76, v44, v44
	v_fmac_f32_e32 v77, v43, v43
	v_fmac_f32_e32 v76, v45, v45
	v_add_f32_e32 v77, v77, v76
	v_add_f32_e32 v70, v70, v77
	s_waitcnt vmcnt(4)
	v_mul_f32_e32 v77, v46, v46
	v_mul_f32_e32 v76, v48, v48
	v_fmac_f32_e32 v77, v47, v47
	v_fmac_f32_e32 v76, v49, v49
	v_add_f32_e32 v77, v77, v76
	v_add_f32_e32 v70, v70, v77
	s_waitcnt vmcnt(3)
	v_mul_f32_e32 v77, v54, v54
	v_mul_f32_e32 v76, v56, v56
	v_fmac_f32_e32 v77, v55, v55
	v_fmac_f32_e32 v76, v57, v57
	v_add_f32_e32 v77, v77, v76
	v_add_f32_e32 v70, v70, v77
	s_waitcnt vmcnt(2)
	v_mul_f32_e32 v77, v58, v58
	v_mul_f32_e32 v76, v60, v60
	v_fmac_f32_e32 v77, v59, v59
	v_fmac_f32_e32 v76, v61, v61
	v_add_f32_e32 v77, v77, v76
	v_add_f32_e32 v70, v70, v77
	s_waitcnt vmcnt(1)
	v_mul_f32_e32 v77, v62, v62
	v_mul_f32_e32 v76, v64, v64
	v_fmac_f32_e32 v77, v63, v63
	v_fmac_f32_e32 v76, v65, v65
	v_add_f32_e32 v77, v77, v76
	v_add_f32_e32 v70, v70, v77
	s_waitcnt vmcnt(0)
	v_mul_f32_e32 v77, v66, v66
	v_mul_f32_e32 v76, v68, v68
	v_fmac_f32_e32 v77, v67, v67
	v_fmac_f32_e32 v76, v69, v69
	v_add_f32_e32 v77, v77, v76
	v_add_f32_e32 v70, v70, v77
	s_nop 1
	v_add_f32_dpp v70, v70, v70 quad_perm:[1,0,3,2] row_mask:0xf bank_mask:0xf bound_ctrl:1
	s_nop 1
	v_add_f32_dpp v70, v70, v70 quad_perm:[2,3,0,1] row_mask:0xf bank_mask:0xf bound_ctrl:1
	s_nop 1
	v_add_f32_dpp v70, v70, v70 row_half_mirror row_mask:0xf bank_mask:0xf bound_ctrl:1
	s_nop 1
	v_add_f32_dpp v70, v70, v70 row_mirror row_mask:0xf bank_mask:0xf bound_ctrl:1
	s_nop 0
	v_readlane_b32 s8, v70, 16
	v_readlane_b32 s9, v70, 48
	v_readlane_b32 s6, v70, 0
	v_readlane_b32 s7, v70, 32
	v_mov_b32_e32 v70, s8
	v_mov_b32_e32 v71, s9
	v_pk_add_f32 v[70:71], s[6:7], v[70:71]
	s_nop 0
	v_add_f32_e32 v70, v70, v71
	v_fmamk_f32 v70, v70, 0x3a000000, v236
	v_cmp_gt_f32_e32 vcc, s13, v70
	v_mul_f32_e32 v71, 0x4b800000, v70
	s_nop 0
	v_cndmask_b32_e32 v70, v70, v71, vcc
	v_rsq_f32_e32 v70, v70
	s_nop 0
	v_mul_f32_e32 v71, 0x45800000, v70
	v_cndmask_b32_e32 v70, v70, v71, vcc
	v_pk_mul_f32 v[38:39], v[38:39], v[70:71] op_sel_hi:[1,0]
	v_pk_mul_f32 v[34:35], v[34:35], v[70:71] op_sel_hi:[1,0]
	v_pk_mul_f32 v[40:41], v[40:41], v[70:71] op_sel_hi:[1,0]
	v_pk_mul_f32 v[38:39], v[10:11], v[38:39]
	v_pk_mul_f32 v[36:37], v[36:37], v[70:71] op_sel_hi:[1,0]
	v_pk_mul_f32 v[34:35], v[2:3], v[34:35]
	v_pk_mul_f32 v[40:41], v[12:13], v[40:41]
	v_cvt_pk_bf16_f32 v38, v38, v39
	v_pk_mul_f32 v[36:37], v[4:5], v[36:37]
	v_cvt_pk_bf16_f32 v39, v40, v41
	global_store_dwordx2 v[50:51], v[38:39], off
	v_cvt_pk_bf16_f32 v34, v34, v35
	v_cvt_pk_bf16_f32 v35, v36, v37
	global_store_dwordx2 v[50:51], v[34:35], off offset:512
	v_pk_mul_f32 v[34:35], v[42:43], v[70:71] op_sel_hi:[1,0]
	v_pk_mul_f32 v[36:37], v[44:45], v[70:71] op_sel_hi:[1,0]
	v_pk_mul_f32 v[34:35], v[6:7], v[34:35]
	v_pk_mul_f32 v[36:37], v[8:9], v[36:37]
	v_cvt_pk_bf16_f32 v34, v34, v35
	v_cmp_lt_i32_e32 vcc, s89, v0
	v_cvt_pk_bf16_f32 v35, v36, v37
	global_store_dwordx2 v[50:51], v[34:35], off offset:1024
	v_pk_mul_f32 v[34:35], v[46:47], v[70:71] op_sel_hi:[1,0]
	v_pk_mul_f32 v[36:37], v[48:49], v[70:71] op_sel_hi:[1,0]
	v_pk_mul_f32 v[34:35], v[14:15], v[34:35]
	v_pk_mul_f32 v[36:37], v[16:17], v[36:37]
	v_cvt_pk_bf16_f32 v34, v34, v35
	s_or_b64 s[40:41], vcc, s[40:41]
	v_cvt_pk_bf16_f32 v35, v36, v37
	global_store_dwordx2 v[50:51], v[34:35], off offset:1536
	v_pk_mul_f32 v[34:35], v[54:55], v[70:71] op_sel_hi:[1,0]
	v_pk_mul_f32 v[36:37], v[56:57], v[70:71] op_sel_hi:[1,0]
	v_pk_mul_f32 v[34:35], v[18:19], v[34:35]
	v_pk_mul_f32 v[36:37], v[20:21], v[36:37]
	v_cvt_pk_bf16_f32 v34, v34, v35
	s_nop 0
	v_cvt_pk_bf16_f32 v35, v36, v37
	global_store_dwordx2 v[50:51], v[34:35], off offset:2048
	v_pk_mul_f32 v[34:35], v[58:59], v[70:71] op_sel_hi:[1,0]
	v_pk_mul_f32 v[36:37], v[60:61], v[70:71] op_sel_hi:[1,0]
	v_pk_mul_f32 v[34:35], v[22:23], v[34:35]
	v_pk_mul_f32 v[36:37], v[24:25], v[36:37]
	v_cvt_pk_bf16_f32 v34, v34, v35
	s_nop 0
	v_cvt_pk_bf16_f32 v35, v36, v37
	global_store_dwordx2 v[50:51], v[34:35], off offset:2560
	v_pk_mul_f32 v[34:35], v[62:63], v[70:71] op_sel_hi:[1,0]
	v_pk_mul_f32 v[36:37], v[64:65], v[70:71] op_sel_hi:[1,0]
	v_pk_mul_f32 v[34:35], v[26:27], v[34:35]
	v_pk_mul_f32 v[36:37], v[28:29], v[36:37]
	v_cvt_pk_bf16_f32 v34, v34, v35
	s_nop 0
	v_cvt_pk_bf16_f32 v35, v36, v37
	global_store_dwordx2 v[50:51], v[34:35], off offset:3072
	v_pk_mul_f32 v[34:35], v[66:67], v[70:71] op_sel_hi:[1,0]
	v_pk_mul_f32 v[36:37], v[68:69], v[70:71] op_sel_hi:[1,0]
	v_pk_mul_f32 v[34:35], v[30:31], v[34:35]
	v_pk_mul_f32 v[36:37], v[32:33], v[36:37]
	v_cvt_pk_bf16_f32 v34, v34, v35
	s_nop 0
	v_cvt_pk_bf16_f32 v35, v36, v37
	global_store_dwordx2 v[50:51], v[34:35], off offset:3584
	v_lshl_add_u64 v[50:51], v[50:51], 0, s[46:47]
	s_andn2_b64 exec, exec, s[40:41]
	s_cbranch_execnz .LBB0_512

.LBB0_555:
	v_add_u32_e32 v0, 0x800, v0
	global_load_dwordx4 v[38:41], v[52:53], off offset:-4096
	global_load_dwordx4 v[34:37], v[52:53], off offset:-3072
	global_load_dwordx4 v[42:45], v[52:53], off offset:-2048
	global_load_dwordx4 v[46:49], v[52:53], off offset:-1024
	global_load_dwordx4 v[54:57], v[52:53], off
	global_load_dwordx4 v[58:61], v[52:53], off offset:1024
	global_load_dwordx4 v[62:65], v[52:53], off offset:2048
	global_load_dwordx4 v[66:69], v[52:53], off offset:3072
	s_nop 0
	v_lshl_add_u64 v[52:53], v[52:53], 0, s[42:43]
	s_waitcnt vmcnt(7)
	v_mul_f32_e32 v70, v38, v38
	v_mul_f32_e32 v76, v40, v40
	v_fmac_f32_e32 v70, v39, v39
	v_fmac_f32_e32 v76, v41, v41
	v_add_f32_e32 v70, v70, v76
	s_waitcnt vmcnt(6)
	v_mul_f32_e32 v77, v34, v34
	v_mul_f32_e32 v76, v36, v36
	v_fmac_f32_e32 v77, v35, v35
	v_fmac_f32_e32 v76, v37, v37
	v_add_f32_e32 v77, v77, v76
	v_add_f32_e32 v70, v70, v77
	s_waitcnt vmcnt(5)
	v_mul_f32_e32 v77, v42, v42
	v_mul_f32_e32 v76, v44, v44
	v_fmac_f32_e32 v77, v43, v43
	v_fmac_f32_e32 v76, v45, v45
	v_add_f32_e32 v77, v77, v76
	v_add_f32_e32 v70, v70, v77
	s_waitcnt vmcnt(4)
	v_mul_f32_e32 v77, v46, v46
	v_mul_f32_e32 v76, v48, v48
	v_fmac_f32_e32 v77, v47, v47
	v_fmac_f32_e32 v76, v49, v49
	v_add_f32_e32 v77, v77, v76
	v_add_f32_e32 v70, v70, v77
	s_waitcnt vmcnt(3)
	v_mul_f32_e32 v77, v54, v54
	v_mul_f32_e32 v76, v56, v56
	v_fmac_f32_e32 v77, v55, v55
	v_fmac_f32_e32 v76, v57, v57
	v_add_f32_e32 v77, v77, v76
	v_add_f32_e32 v70, v70, v77
	s_waitcnt vmcnt(2)
	v_mul_f32_e32 v77, v58, v58
	v_mul_f32_e32 v76, v60, v60
	v_fmac_f32_e32 v77, v59, v59
	v_fmac_f32_e32 v76, v61, v61
	v_add_f32_e32 v77, v77, v76
	v_add_f32_e32 v70, v70, v77
	s_waitcnt vmcnt(1)
	v_mul_f32_e32 v77, v62, v62
	v_mul_f32_e32 v76, v64, v64
	v_fmac_f32_e32 v77, v63, v63
	v_fmac_f32_e32 v76, v65, v65
	v_add_f32_e32 v77, v77, v76
	v_add_f32_e32 v70, v70, v77
	s_waitcnt vmcnt(0)
	v_mul_f32_e32 v77, v66, v66
	v_mul_f32_e32 v76, v68, v68
	v_fmac_f32_e32 v77, v67, v67
	v_fmac_f32_e32 v76, v69, v69
	v_add_f32_e32 v77, v77, v76
	v_add_f32_e32 v70, v70, v77
	s_nop 1
	v_add_f32_dpp v70, v70, v70 quad_perm:[1,0,3,2] row_mask:0xf bank_mask:0xf bound_ctrl:1
	s_nop 1
	v_add_f32_dpp v70, v70, v70 quad_perm:[2,3,0,1] row_mask:0xf bank_mask:0xf bound_ctrl:1
	s_nop 1
	v_add_f32_dpp v70, v70, v70 row_half_mirror row_mask:0xf bank_mask:0xf bound_ctrl:1
	s_nop 1
	v_add_f32_dpp v70, v70, v70 row_mirror row_mask:0xf bank_mask:0xf bound_ctrl:1
	s_nop 0
	v_readlane_b32 s8, v70, 16
	v_readlane_b32 s9, v70, 48
	v_readlane_b32 s6, v70, 0
	v_readlane_b32 s7, v70, 32
	v_mov_b32_e32 v70, s8
	v_mov_b32_e32 v71, s9
	v_pk_add_f32 v[70:71], s[6:7], v[70:71]
	s_nop 0
	v_add_f32_e32 v70, v70, v71
	v_fmamk_f32 v70, v70, 0x3a000000, v236
	v_cmp_gt_f32_e32 vcc, s13, v70
	v_mul_f32_e32 v71, 0x4b800000, v70
	s_nop 0
	v_cndmask_b32_e32 v70, v70, v71, vcc
	v_rsq_f32_e32 v70, v70
	s_nop 0
	v_mul_f32_e32 v71, 0x45800000, v70
	v_cndmask_b32_e32 v70, v70, v71, vcc
	v_pk_mul_f32 v[38:39], v[38:39], v[70:71] op_sel_hi:[1,0]
	v_pk_mul_f32 v[34:35], v[34:35], v[70:71] op_sel_hi:[1,0]
	v_pk_mul_f32 v[40:41], v[40:41], v[70:71] op_sel_hi:[1,0]
	v_pk_mul_f32 v[38:39], v[2:3], v[38:39]
	v_pk_mul_f32 v[36:37], v[36:37], v[70:71] op_sel_hi:[1,0]
	v_pk_mul_f32 v[34:35], v[6:7], v[34:35]
	v_pk_mul_f32 v[40:41], v[4:5], v[40:41]
	v_cvt_pk_bf16_f32 v38, v38, v39
	v_pk_mul_f32 v[36:37], v[8:9], v[36:37]
	v_cvt_pk_bf16_f32 v39, v40, v41
	global_store_dwordx2 v[50:51], v[38:39], off
	v_cvt_pk_bf16_f32 v34, v34, v35
	v_cvt_pk_bf16_f32 v35, v36, v37
	global_store_dwordx2 v[50:51], v[34:35], off offset:512
	v_pk_mul_f32 v[34:35], v[42:43], v[70:71] op_sel_hi:[1,0]
	v_pk_mul_f32 v[36:37], v[44:45], v[70:71] op_sel_hi:[1,0]
	v_pk_mul_f32 v[34:35], v[10:11], v[34:35]
	v_pk_mul_f32 v[36:37], v[12:13], v[36:37]
	v_cvt_pk_bf16_f32 v34, v34, v35
	v_cmp_lt_i32_e32 vcc, s89, v0
	v_cvt_pk_bf16_f32 v35, v36, v37
	global_store_dwordx2 v[50:51], v[34:35], off offset:1024
	v_pk_mul_f32 v[34:35], v[46:47], v[70:71] op_sel_hi:[1,0]
	v_pk_mul_f32 v[36:37], v[48:49], v[70:71] op_sel_hi:[1,0]
	v_pk_mul_f32 v[34:35], v[14:15], v[34:35]
	v_pk_mul_f32 v[36:37], v[16:17], v[36:37]
	v_cvt_pk_bf16_f32 v34, v34, v35
	s_or_b64 s[40:41], vcc, s[40:41]
	v_cvt_pk_bf16_f32 v35, v36, v37
	global_store_dwordx2 v[50:51], v[34:35], off offset:1536
	v_pk_mul_f32 v[34:35], v[54:55], v[70:71] op_sel_hi:[1,0]
	v_pk_mul_f32 v[36:37], v[56:57], v[70:71] op_sel_hi:[1,0]
	v_pk_mul_f32 v[34:35], v[18:19], v[34:35]
	v_pk_mul_f32 v[36:37], v[20:21], v[36:37]
	v_cvt_pk_bf16_f32 v34, v34, v35
	s_nop 0
	v_cvt_pk_bf16_f32 v35, v36, v37
	global_store_dwordx2 v[50:51], v[34:35], off offset:2048
	v_pk_mul_f32 v[34:35], v[58:59], v[70:71] op_sel_hi:[1,0]
	v_pk_mul_f32 v[36:37], v[60:61], v[70:71] op_sel_hi:[1,0]
	v_pk_mul_f32 v[34:35], v[22:23], v[34:35]
	v_pk_mul_f32 v[36:37], v[24:25], v[36:37]
	v_cvt_pk_bf16_f32 v34, v34, v35
	s_nop 0
	v_cvt_pk_bf16_f32 v35, v36, v37
	global_store_dwordx2 v[50:51], v[34:35], off offset:2560
	v_pk_mul_f32 v[34:35], v[62:63], v[70:71] op_sel_hi:[1,0]
	v_pk_mul_f32 v[36:37], v[64:65], v[70:71] op_sel_hi:[1,0]
	v_pk_mul_f32 v[34:35], v[26:27], v[34:35]
	v_pk_mul_f32 v[36:37], v[28:29], v[36:37]
	v_cvt_pk_bf16_f32 v34, v34, v35
	s_nop 0
	v_cvt_pk_bf16_f32 v35, v36, v37
	global_store_dwordx2 v[50:51], v[34:35], off offset:3072
	v_pk_mul_f32 v[34:35], v[66:67], v[70:71] op_sel_hi:[1,0]
	v_pk_mul_f32 v[36:37], v[68:69], v[70:71] op_sel_hi:[1,0]
	v_pk_mul_f32 v[34:35], v[30:31], v[34:35]
	v_pk_mul_f32 v[36:37], v[32:33], v[36:37]
	v_cvt_pk_bf16_f32 v34, v34, v35
	s_nop 0
	v_cvt_pk_bf16_f32 v35, v36, v37
	global_store_dwordx2 v[50:51], v[34:35], off offset:3584
	v_lshl_add_u64 v[50:51], v[50:51], 0, s[46:47]
	s_andn2_b64 exec, exec, s[40:41]
	s_cbranch_execnz .LBB0_555
